# v017 + back-edge rotation: loop counter / exit test / header flags moved into the last MFMA segment of the FFN-up and FFN-down main loops
# baseline (speedup 1.0000x reference)
.Lsp_LBB0269:
	v_add_u32_e32 v143, 0x10000, v140
	ds_read_b128 v[136:139], v143
	ds_read_b128 v[144:147], v143 offset:1024
	ds_read_b128 v[148:151], v143 offset:2048
	ds_read_b128 v[152:155], v143 offset:3072
	v_add_u32_e32 v143, 0x14000, v140
	ds_read_b128 v[168:171], v143
	ds_read_b128 v[172:175], v143 offset:1024
	ds_read_b128 v[176:179], v143 offset:2048
	ds_read_b128 v[180:183], v143 offset:3072
	ds_read_b128 v[184:187], v142
	ds_read_b128 v[188:191], v142 offset:1024
	ds_read_b128 v[192:195], v142 offset:2048
	ds_read_b128 v[196:199], v142 offset:3072
	ds_read_b128 v[200:203], v142 offset:4096
	ds_read_b128 v[204:207], v142 offset:5120
	ds_read_b128 v[216:219], v142 offset:6144
	ds_read_b128 v[220:223], v142 offset:7168
	s_or_b32 s54, s35, 1
	s_lshl_b64 s[16:17], s[54:55], 7
	s_add_i32 s54, s35, 2
	s_lshl_b64 s[44:45], s[54:55], 7
	s_add_u32 s46, s66, s44
	s_addc_u32 s47, s67, s45
	s_and_b64 vcc, s[14:15], exec
	s_cselect_b32 vcc_hi, s29, s47
	s_cselect_b32 vcc_lo, s65, s46
	s_add_u32 s44, s70, s44
	s_addc_u32 s45, s71, s45
	s_and_b64 s[14:15], s[14:15], exec
	s_cselect_b32 s15, s51, s45
	s_cselect_b32 s14, s30, s44
	s_add_i32 s44, 0, 0x10000
	s_add_i32 s45, 0, 0x14000
	s_add_i32 m0, s73, 0xc000
	s_add_u32 s16, s31, s16
	s_addc_u32 s17, s34, s17
	global_load_lds_dwordx4 v130, s[16:17]
	s_add_i32 m0, s73, 0xe000
	s_nop 0
	global_load_lds_dwordx4 v132, s[16:17]
	s_waitcnt vmcnt(8)
	s_waitcnt lgkmcnt(0)
	s_barrier
	s_waitcnt lgkmcnt(0)
	v_mfma_f32_16x16x32_bf16 v[122:125], v[136:139], v[184:187], v[122:125]
	v_mfma_f32_16x16x32_bf16 v[122:125], v[144:147], v[188:191], v[122:125]
	v_mfma_f32_16x16x32_bf16 v[114:117], v[148:151], v[184:187], v[114:117]
	v_mfma_f32_16x16x32_bf16 v[114:117], v[152:155], v[188:191], v[114:117]
	v_mfma_f32_16x16x32_bf16 v[106:109], v[136:139], v[192:195], v[106:109]
	v_mfma_f32_16x16x32_bf16 v[106:109], v[144:147], v[196:199], v[106:109]
	v_mfma_f32_16x16x32_bf16 v[102:105], v[148:151], v[192:195], v[102:105]
	v_mfma_f32_16x16x32_bf16 v[102:105], v[152:155], v[196:199], v[102:105]
	v_mfma_f32_16x16x32_bf16 v[90:93], v[136:139], v[200:203], v[90:93]
	v_mfma_f32_16x16x32_bf16 v[90:93], v[144:147], v[204:207], v[90:93]
	v_mfma_f32_16x16x32_bf16 v[86:89], v[148:151], v[200:203], v[86:89]
	v_mfma_f32_16x16x32_bf16 v[86:89], v[152:155], v[204:207], v[86:89]
	v_mfma_f32_16x16x32_bf16 v[74:77], v[136:139], v[216:219], v[74:77]
	v_mfma_f32_16x16x32_bf16 v[74:77], v[144:147], v[220:223], v[74:77]
	v_mfma_f32_16x16x32_bf16 v[70:73], v[148:151], v[216:219], v[70:73]
	v_mfma_f32_16x16x32_bf16 v[70:73], v[152:155], v[220:223], v[70:73]
	v_mfma_f32_16x16x32_bf16 v[126:129], v[168:171], v[184:187], v[126:129]
	v_mfma_f32_16x16x32_bf16 v[126:129], v[172:175], v[188:191], v[126:129]
	v_mfma_f32_16x16x32_bf16 v[118:121], v[176:179], v[184:187], v[118:121]
	v_mfma_f32_16x16x32_bf16 v[118:121], v[180:183], v[188:191], v[118:121]
	v_mfma_f32_16x16x32_bf16 v[110:113], v[168:171], v[192:195], v[110:113]
	v_mfma_f32_16x16x32_bf16 v[110:113], v[172:175], v[196:199], v[110:113]
	v_mfma_f32_16x16x32_bf16 v[98:101], v[176:179], v[192:195], v[98:101]
	v_mfma_f32_16x16x32_bf16 v[98:101], v[180:183], v[196:199], v[98:101]
	v_mfma_f32_16x16x32_bf16 v[94:97], v[168:171], v[200:203], v[94:97]
	v_mfma_f32_16x16x32_bf16 v[94:97], v[172:175], v[204:207], v[94:97]
	v_mfma_f32_16x16x32_bf16 v[82:85], v[176:179], v[200:203], v[82:85]
	v_mfma_f32_16x16x32_bf16 v[82:85], v[180:183], v[204:207], v[82:85]
	v_mfma_f32_16x16x32_bf16 v[78:81], v[168:171], v[216:219], v[78:81]
	v_mfma_f32_16x16x32_bf16 v[78:81], v[172:175], v[220:223], v[78:81]
	v_mfma_f32_16x16x32_bf16 v[66:69], v[176:179], v[216:219], v[66:69]
	v_mfma_f32_16x16x32_bf16 v[66:69], v[180:183], v[220:223], v[66:69]
	s_barrier
	s_add_i32 s16, s44, s61
	s_mov_b32 m0, s16
	ds_read_b128 v[184:187], v142 offset:16384
	ds_read_b128 v[188:191], v142 offset:17408
	ds_read_b128 v[192:195], v142 offset:18432
	ds_read_b128 v[196:199], v142 offset:19456
	ds_read_b128 v[200:203], v142 offset:20480
	ds_read_b128 v[204:207], v142 offset:21504
	ds_read_b128 v[216:219], v142 offset:22528
	ds_read_b128 v[220:223], v142 offset:23552
	global_load_lds_dwordx4 v158, s[14:15]
	s_add_i32 m0, s16, 0x2000
	s_nop 0
	global_load_lds_dwordx4 v134, s[14:15]
	s_add_u32 s16, s14, 0x80000
	s_addc_u32 s17, s15, 0
	s_add_i32 s44, s45, s61
	s_mov_b32 m0, s44
	s_nop 0
	global_load_lds_dwordx4 v158, s[16:17]
	s_add_i32 m0, s44, 0x2000
	s_nop 0
	global_load_lds_dwordx4 v134, s[16:17]
	s_mov_b32 m0, s73
	s_nop 0
	global_load_lds_dwordx4 v130, vcc
	s_mov_b32 m0, s75
	s_nop 0
	global_load_lds_dwordx4 v132, vcc
	s_waitcnt vmcnt(8)
	s_waitcnt lgkmcnt(0)
	s_barrier
	s_waitcnt lgkmcnt(0)
	v_mfma_f32_16x16x32_bf16 v[58:61], v[136:139], v[184:187], v[58:61]
	v_mfma_f32_16x16x32_bf16 v[58:61], v[144:147], v[188:191], v[58:61]
	v_mfma_f32_16x16x32_bf16 v[54:57], v[148:151], v[184:187], v[54:57]
	v_mfma_f32_16x16x32_bf16 v[54:57], v[152:155], v[188:191], v[54:57]
	v_mfma_f32_16x16x32_bf16 v[42:45], v[136:139], v[192:195], v[42:45]
	v_mfma_f32_16x16x32_bf16 v[42:45], v[144:147], v[196:199], v[42:45]
	v_mfma_f32_16x16x32_bf16 v[38:41], v[148:151], v[192:195], v[38:41]
	v_mfma_f32_16x16x32_bf16 v[38:41], v[152:155], v[196:199], v[38:41]
	v_mfma_f32_16x16x32_bf16 v[26:29], v[136:139], v[200:203], v[26:29]
	v_mfma_f32_16x16x32_bf16 v[26:29], v[144:147], v[204:207], v[26:29]
	v_mfma_f32_16x16x32_bf16 v[22:25], v[148:151], v[200:203], v[22:25]
	v_mfma_f32_16x16x32_bf16 v[22:25], v[152:155], v[204:207], v[22:25]
	v_mfma_f32_16x16x32_bf16 v[10:13], v[136:139], v[216:219], v[10:13]
	v_mfma_f32_16x16x32_bf16 v[10:13], v[144:147], v[220:223], v[10:13]
	v_mfma_f32_16x16x32_bf16 v[2:5], v[148:151], v[216:219], v[2:5]
	v_mfma_f32_16x16x32_bf16 v[2:5], v[152:155], v[220:223], v[2:5]
	v_mfma_f32_16x16x32_bf16 v[62:65], v[168:171], v[184:187], v[62:65]
	v_mfma_f32_16x16x32_bf16 v[62:65], v[172:175], v[188:191], v[62:65]
	v_mfma_f32_16x16x32_bf16 v[50:53], v[176:179], v[184:187], v[50:53]
	v_mfma_f32_16x16x32_bf16 v[50:53], v[180:183], v[188:191], v[50:53]
	v_mfma_f32_16x16x32_bf16 v[46:49], v[168:171], v[192:195], v[46:49]
	v_mfma_f32_16x16x32_bf16 v[46:49], v[172:175], v[196:199], v[46:49]
	v_mfma_f32_16x16x32_bf16 v[34:37], v[176:179], v[192:195], v[34:37]
	v_mfma_f32_16x16x32_bf16 v[34:37], v[180:183], v[196:199], v[34:37]
	v_mfma_f32_16x16x32_bf16 v[30:33], v[168:171], v[200:203], v[30:33]
	v_mfma_f32_16x16x32_bf16 v[30:33], v[172:175], v[204:207], v[30:33]
	v_mfma_f32_16x16x32_bf16 v[18:21], v[176:179], v[200:203], v[18:21]
	v_mfma_f32_16x16x32_bf16 v[18:21], v[180:183], v[204:207], v[18:21]
	v_mfma_f32_16x16x32_bf16 v[14:17], v[168:171], v[216:219], v[14:17]
	v_mfma_f32_16x16x32_bf16 v[14:17], v[172:175], v[220:223], v[14:17]
	v_mfma_f32_16x16x32_bf16 v[6:9], v[176:179], v[216:219], v[6:9]
	v_mfma_f32_16x16x32_bf16 v[6:9], v[180:183], v[220:223], v[6:9]
	s_barrier
	s_add_i32 s44, 0, 0x18000
	s_add_i32 s45, 0, 0x1c000
	s_add_u32 s16, vcc_lo, 0x80000
	s_addc_u32 s17, vcc_hi, 0
	s_mov_b32 m0, s24
	v_add_u32_e32 v143, s44, v140
	ds_read_b128 v[136:139], v143
	ds_read_b128 v[144:147], v143 offset:1024
	ds_read_b128 v[148:151], v143 offset:2048
	ds_read_b128 v[152:155], v143 offset:3072
	v_add_u32_e32 v143, s45, v140
	ds_read_b128 v[168:171], v143
	ds_read_b128 v[172:175], v143 offset:1024
	ds_read_b128 v[176:179], v143 offset:2048
	ds_read_b128 v[180:183], v143 offset:3072
	ds_read_b128 v[184:187], v142 offset:32768
	ds_read_b128 v[188:191], v142 offset:33792
	ds_read_b128 v[192:195], v142 offset:34816
	ds_read_b128 v[196:199], v142 offset:35840
	ds_read_b128 v[200:203], v142 offset:36864
	ds_read_b128 v[204:207], v142 offset:37888
	ds_read_b128 v[216:219], v142 offset:38912
	ds_read_b128 v[220:223], v142 offset:39936
	global_load_lds_dwordx4 v130, s[16:17]
	s_mov_b32 m0, s25
	s_nop 0
	global_load_lds_dwordx4 v132, s[16:17]
	s_waitcnt vmcnt(8)
	s_waitcnt lgkmcnt(0)
	s_barrier
	s_waitcnt lgkmcnt(0)
	v_mfma_f32_16x16x32_bf16 v[122:125], v[136:139], v[184:187], v[122:125]
	v_mfma_f32_16x16x32_bf16 v[122:125], v[144:147], v[188:191], v[122:125]
	v_mfma_f32_16x16x32_bf16 v[114:117], v[148:151], v[184:187], v[114:117]
	v_mfma_f32_16x16x32_bf16 v[114:117], v[152:155], v[188:191], v[114:117]
	v_mfma_f32_16x16x32_bf16 v[106:109], v[136:139], v[192:195], v[106:109]
	v_mfma_f32_16x16x32_bf16 v[106:109], v[144:147], v[196:199], v[106:109]
	v_mfma_f32_16x16x32_bf16 v[102:105], v[148:151], v[192:195], v[102:105]
	v_mfma_f32_16x16x32_bf16 v[102:105], v[152:155], v[196:199], v[102:105]
	v_mfma_f32_16x16x32_bf16 v[90:93], v[136:139], v[200:203], v[90:93]
	v_mfma_f32_16x16x32_bf16 v[90:93], v[144:147], v[204:207], v[90:93]
	v_mfma_f32_16x16x32_bf16 v[86:89], v[148:151], v[200:203], v[86:89]
	v_mfma_f32_16x16x32_bf16 v[86:89], v[152:155], v[204:207], v[86:89]
	v_mfma_f32_16x16x32_bf16 v[74:77], v[136:139], v[216:219], v[74:77]
	v_mfma_f32_16x16x32_bf16 v[74:77], v[144:147], v[220:223], v[74:77]
	v_mfma_f32_16x16x32_bf16 v[70:73], v[148:151], v[216:219], v[70:73]
	v_mfma_f32_16x16x32_bf16 v[70:73], v[152:155], v[220:223], v[70:73]
	v_mfma_f32_16x16x32_bf16 v[126:129], v[168:171], v[184:187], v[126:129]
	v_mfma_f32_16x16x32_bf16 v[126:129], v[172:175], v[188:191], v[126:129]
	v_mfma_f32_16x16x32_bf16 v[118:121], v[176:179], v[184:187], v[118:121]
	v_mfma_f32_16x16x32_bf16 v[118:121], v[180:183], v[188:191], v[118:121]
	v_mfma_f32_16x16x32_bf16 v[110:113], v[168:171], v[192:195], v[110:113]
	v_mfma_f32_16x16x32_bf16 v[110:113], v[172:175], v[196:199], v[110:113]
	v_mfma_f32_16x16x32_bf16 v[98:101], v[176:179], v[192:195], v[98:101]
	v_mfma_f32_16x16x32_bf16 v[98:101], v[180:183], v[196:199], v[98:101]
	v_mfma_f32_16x16x32_bf16 v[94:97], v[168:171], v[200:203], v[94:97]
	v_mfma_f32_16x16x32_bf16 v[94:97], v[172:175], v[204:207], v[94:97]
	v_mfma_f32_16x16x32_bf16 v[82:85], v[176:179], v[200:203], v[82:85]
	v_mfma_f32_16x16x32_bf16 v[82:85], v[180:183], v[204:207], v[82:85]
	v_mfma_f32_16x16x32_bf16 v[78:81], v[168:171], v[216:219], v[78:81]
	v_mfma_f32_16x16x32_bf16 v[78:81], v[172:175], v[220:223], v[78:81]
	v_mfma_f32_16x16x32_bf16 v[66:69], v[176:179], v[216:219], v[66:69]
	v_mfma_f32_16x16x32_bf16 v[66:69], v[180:183], v[220:223], v[66:69]
	s_barrier
	s_add_i32 s16, s44, s61
	s_mov_b32 m0, s16
	s_add_u32 s14, s14, 0x80
	s_addc_u32 s15, s15, 0
	s_add_u32 vcc_lo, vcc_lo, 0x80
	s_addc_u32 vcc_hi, vcc_hi, 0
	ds_read_b128 v[184:187], v142 offset:49152
	ds_read_b128 v[188:191], v142 offset:50176
	ds_read_b128 v[192:195], v142 offset:51200
	ds_read_b128 v[196:199], v142 offset:52224
	ds_read_b128 v[200:203], v142 offset:53248
	ds_read_b128 v[204:207], v142 offset:54272
	ds_read_b128 v[216:219], v142 offset:55296
	ds_read_b128 v[220:223], v142 offset:56320
	global_load_lds_dwordx4 v158, s[14:15]
	s_add_i32 m0, s16, 0x2000
	s_nop 0
	global_load_lds_dwordx4 v134, s[14:15]
	s_add_u32 s14, s14, 0x80000
	s_addc_u32 s15, s15, 0
	s_add_i32 s16, s45, s61
	s_mov_b32 m0, s16
	s_nop 0
	global_load_lds_dwordx4 v158, s[14:15]
	s_add_i32 m0, s16, 0x2000
	s_nop 0
	global_load_lds_dwordx4 v134, s[14:15]
	s_mov_b32 m0, s26
	s_nop 0
	global_load_lds_dwordx4 v130, vcc
	s_mov_b32 m0, s27
	s_nop 0
	global_load_lds_dwordx4 v132, vcc
	s_waitcnt vmcnt(8)
	s_waitcnt lgkmcnt(0)
	s_barrier
	s_waitcnt lgkmcnt(0)
	v_mfma_f32_16x16x32_bf16 v[58:61], v[136:139], v[184:187], v[58:61]
	v_mfma_f32_16x16x32_bf16 v[58:61], v[144:147], v[188:191], v[58:61]
	v_mfma_f32_16x16x32_bf16 v[54:57], v[148:151], v[184:187], v[54:57]
	v_mfma_f32_16x16x32_bf16 v[54:57], v[152:155], v[188:191], v[54:57]
	v_mfma_f32_16x16x32_bf16 v[42:45], v[136:139], v[192:195], v[42:45]
	v_mfma_f32_16x16x32_bf16 v[42:45], v[144:147], v[196:199], v[42:45]
	v_mfma_f32_16x16x32_bf16 v[38:41], v[148:151], v[192:195], v[38:41]
	v_mfma_f32_16x16x32_bf16 v[38:41], v[152:155], v[196:199], v[38:41]
	v_mfma_f32_16x16x32_bf16 v[26:29], v[136:139], v[200:203], v[26:29]
	v_mfma_f32_16x16x32_bf16 v[26:29], v[144:147], v[204:207], v[26:29]
	v_mfma_f32_16x16x32_bf16 v[22:25], v[148:151], v[200:203], v[22:25]
	v_mfma_f32_16x16x32_bf16 v[22:25], v[152:155], v[204:207], v[22:25]
	v_mfma_f32_16x16x32_bf16 v[10:13], v[136:139], v[216:219], v[10:13]
	v_mfma_f32_16x16x32_bf16 v[10:13], v[144:147], v[220:223], v[10:13]
	v_mfma_f32_16x16x32_bf16 v[2:5], v[148:151], v[216:219], v[2:5]
	v_mfma_f32_16x16x32_bf16 v[2:5], v[152:155], v[220:223], v[2:5]
	v_mfma_f32_16x16x32_bf16 v[62:65], v[168:171], v[184:187], v[62:65]
	v_mfma_f32_16x16x32_bf16 v[62:65], v[172:175], v[188:191], v[62:65]
	s_cmp_gt_u32 s35, 29
	v_mfma_f32_16x16x32_bf16 v[50:53], v[176:179], v[184:187], v[50:53]
	s_cselect_b32 s32, 1, 0
	v_mfma_f32_16x16x32_bf16 v[50:53], v[180:183], v[188:191], v[50:53]
	s_mov_b32 s35, s54
	v_mfma_f32_16x16x32_bf16 v[46:49], v[168:171], v[192:195], v[46:49]
	s_cmp_eq_u32 s35, 30
	v_mfma_f32_16x16x32_bf16 v[46:49], v[172:175], v[196:199], v[46:49]
	s_cselect_b64 s[14:15], -1, 0
	v_mfma_f32_16x16x32_bf16 v[34:37], v[176:179], v[192:195], v[34:37]
	s_and_b64 s[16:17], s[68:69], s[14:15]
	v_mfma_f32_16x16x32_bf16 v[34:37], v[180:183], v[196:199], v[34:37]
	s_and_b64 s[16:17], s[16:17], s[8:9]
	v_mfma_f32_16x16x32_bf16 v[30:33], v[168:171], v[200:203], v[30:33]
	s_and_b64 s[16:17], s[16:17], s[92:93]
	v_mfma_f32_16x16x32_bf16 v[30:33], v[172:175], v[204:207], v[30:33]
	s_cmp_lg_u64 s[16:17], 0
	v_mfma_f32_16x16x32_bf16 v[18:21], v[176:179], v[200:203], v[18:21]
	s_cselect_b32 s16, 2, 0
	v_mfma_f32_16x16x32_bf16 v[18:21], v[180:183], v[204:207], v[18:21]
	s_or_b32 s32, s32, s16
	v_mfma_f32_16x16x32_bf16 v[14:17], v[168:171], v[216:219], v[14:17]
	v_mfma_f32_16x16x32_bf16 v[14:17], v[172:175], v[220:223], v[14:17]
	v_mfma_f32_16x16x32_bf16 v[6:9], v[176:179], v[216:219], v[6:9]
	v_mfma_f32_16x16x32_bf16 v[6:9], v[180:183], v[220:223], v[6:9]
	s_barrier
	s_cmp_eq_u32 s32, 0
	s_cbranch_scc1 .Lsp_LBB0269
	s_bitcmp1_b32 s32, 0
	s_cbranch_scc1 .LBB0_279

.Lsp_LBB0353:
	s_add_u32 s36, s0, 0x100
	s_addc_u32 s37, s1, 0
	s_add_i32 s27, 0, 0x10000
	s_cmpk_eq_i32 s26, 0x52
	s_cselect_b32 s69, s65, s37
	s_cselect_b32 s68, s64, s36
	v_add_u32_e32 v144, s27, v146
	s_cselect_b32 s15, s67, s25
	s_cselect_b32 s14, s66, s24
	s_add_i32 s28, 0, 0x14000
	ds_read_b128 v[140:143], v144
	ds_read_b128 v[150:153], v144 offset:1024
	ds_read_b128 v[154:157], v144 offset:2048
	ds_read_b128 v[168:171], v144 offset:3072
	v_add_u32_e32 v144, s28, v146
	ds_read_b128 v[172:175], v144
	ds_read_b128 v[176:179], v144 offset:1024
	ds_read_b128 v[180:183], v144 offset:2048
	ds_read_b128 v[184:187], v144 offset:3072
	s_add_i32 m0, s59, 0xc000
	ds_read_b128 v[188:191], v148
	ds_read_b128 v[192:195], v148 offset:1024
	ds_read_b128 v[196:199], v148 offset:2048
	ds_read_b128 v[200:203], v148 offset:3072
	ds_read_b128 v[204:207], v148 offset:4096
	ds_read_b128 v[216:219], v148 offset:5120
	ds_read_b128 v[220:223], v148 offset:6144
	ds_read_b128 v[224:227], v148 offset:7168
	global_load_lds_dwordx4 v136, s[0:1]
	s_add_i32 m0, s59, 0xe000
	s_nop 0
	global_load_lds_dwordx4 v138, s[0:1]
	s_waitcnt vmcnt(8)
	s_waitcnt lgkmcnt(0)
	s_barrier
	s_waitcnt lgkmcnt(0)
	v_mfma_f32_16x16x32_bf16 v[126:129], v[140:143], v[188:191], v[126:129]
	v_mfma_f32_16x16x32_bf16 v[126:129], v[150:153], v[192:195], v[126:129]
	v_mfma_f32_16x16x32_bf16 v[122:125], v[154:157], v[188:191], v[122:125]
	v_mfma_f32_16x16x32_bf16 v[122:125], v[168:171], v[192:195], v[122:125]
	v_mfma_f32_16x16x32_bf16 v[110:113], v[140:143], v[196:199], v[110:113]
	v_mfma_f32_16x16x32_bf16 v[110:113], v[150:153], v[200:203], v[110:113]
	v_mfma_f32_16x16x32_bf16 v[106:109], v[154:157], v[196:199], v[106:109]
	v_mfma_f32_16x16x32_bf16 v[106:109], v[168:171], v[200:203], v[106:109]
	v_mfma_f32_16x16x32_bf16 v[94:97], v[140:143], v[204:207], v[94:97]
	v_mfma_f32_16x16x32_bf16 v[94:97], v[150:153], v[216:219], v[94:97]
	v_mfma_f32_16x16x32_bf16 v[90:93], v[154:157], v[204:207], v[90:93]
	v_mfma_f32_16x16x32_bf16 v[90:93], v[168:171], v[216:219], v[90:93]
	v_mfma_f32_16x16x32_bf16 v[78:81], v[140:143], v[220:223], v[78:81]
	v_mfma_f32_16x16x32_bf16 v[78:81], v[150:153], v[224:227], v[78:81]
	v_mfma_f32_16x16x32_bf16 v[74:77], v[154:157], v[220:223], v[74:77]
	v_mfma_f32_16x16x32_bf16 v[74:77], v[168:171], v[224:227], v[74:77]
	v_mfma_f32_16x16x32_bf16 v[118:121], v[172:175], v[188:191], v[118:121]
	v_mfma_f32_16x16x32_bf16 v[118:121], v[176:179], v[192:195], v[118:121]
	v_mfma_f32_16x16x32_bf16 v[114:117], v[180:183], v[188:191], v[114:117]
	v_mfma_f32_16x16x32_bf16 v[114:117], v[184:187], v[192:195], v[114:117]
	v_mfma_f32_16x16x32_bf16 v[102:105], v[172:175], v[196:199], v[102:105]
	v_mfma_f32_16x16x32_bf16 v[102:105], v[176:179], v[200:203], v[102:105]
	v_mfma_f32_16x16x32_bf16 v[98:101], v[180:183], v[196:199], v[98:101]
	v_mfma_f32_16x16x32_bf16 v[98:101], v[184:187], v[200:203], v[98:101]
	v_mfma_f32_16x16x32_bf16 v[86:89], v[172:175], v[204:207], v[86:89]
	v_mfma_f32_16x16x32_bf16 v[86:89], v[176:179], v[216:219], v[86:89]
	v_mfma_f32_16x16x32_bf16 v[82:85], v[180:183], v[204:207], v[82:85]
	v_mfma_f32_16x16x32_bf16 v[82:85], v[184:187], v[216:219], v[82:85]
	v_mfma_f32_16x16x32_bf16 v[70:73], v[172:175], v[220:223], v[70:73]
	v_mfma_f32_16x16x32_bf16 v[70:73], v[176:179], v[224:227], v[70:73]
	v_mfma_f32_16x16x32_bf16 v[66:69], v[180:183], v[220:223], v[66:69]
	v_mfma_f32_16x16x32_bf16 v[66:69], v[184:187], v[224:227], v[66:69]
	s_barrier
	s_add_i32 s0, s27, s58
	s_mov_b32 m0, s0
	ds_read_b128 v[188:191], v148 offset:16384
	ds_read_b128 v[192:195], v148 offset:17408
	ds_read_b128 v[196:199], v148 offset:18432
	ds_read_b128 v[200:203], v148 offset:19456
	ds_read_b128 v[204:207], v148 offset:20480
	ds_read_b128 v[216:219], v148 offset:21504
	ds_read_b128 v[220:223], v148 offset:22528
	ds_read_b128 v[224:227], v148 offset:23552
	global_load_lds_dwordx4 v158, s[14:15]
	s_add_i32 m0, s0, 0x2000
	s_add_u32 s0, s14, 0x158000
	s_addc_u32 s1, s15, 0
	s_add_i32 s27, s28, s58
	global_load_lds_dwordx4 v134, s[14:15]
	s_mov_b32 m0, s27
	s_nop 0
	global_load_lds_dwordx4 v158, s[0:1]
	s_add_i32 m0, s27, 0x2000
	s_nop 0
	global_load_lds_dwordx4 v134, s[0:1]
	s_mov_b32 m0, s59
	s_nop 0
	global_load_lds_dwordx4 v130, s[68:69]
	s_mov_b32 m0, s70
	s_nop 0
	global_load_lds_dwordx4 v132, s[68:69]
	s_waitcnt vmcnt(8)
	s_waitcnt lgkmcnt(0)
	s_barrier
	s_waitcnt lgkmcnt(0)
	v_mfma_f32_16x16x32_bf16 v[62:65], v[140:143], v[188:191], v[62:65]
	v_mfma_f32_16x16x32_bf16 v[62:65], v[150:153], v[192:195], v[62:65]
	v_mfma_f32_16x16x32_bf16 v[58:61], v[154:157], v[188:191], v[58:61]
	v_mfma_f32_16x16x32_bf16 v[58:61], v[168:171], v[192:195], v[58:61]
	v_mfma_f32_16x16x32_bf16 v[46:49], v[140:143], v[196:199], v[46:49]
	v_mfma_f32_16x16x32_bf16 v[46:49], v[150:153], v[200:203], v[46:49]
	v_mfma_f32_16x16x32_bf16 v[42:45], v[154:157], v[196:199], v[42:45]
	v_mfma_f32_16x16x32_bf16 v[42:45], v[168:171], v[200:203], v[42:45]
	v_mfma_f32_16x16x32_bf16 v[30:33], v[140:143], v[204:207], v[30:33]
	v_mfma_f32_16x16x32_bf16 v[30:33], v[150:153], v[216:219], v[30:33]
	v_mfma_f32_16x16x32_bf16 v[26:29], v[154:157], v[204:207], v[26:29]
	v_mfma_f32_16x16x32_bf16 v[26:29], v[168:171], v[216:219], v[26:29]
	v_mfma_f32_16x16x32_bf16 v[14:17], v[140:143], v[220:223], v[14:17]
	v_mfma_f32_16x16x32_bf16 v[14:17], v[150:153], v[224:227], v[14:17]
	v_mfma_f32_16x16x32_bf16 v[10:13], v[154:157], v[220:223], v[10:13]
	v_mfma_f32_16x16x32_bf16 v[10:13], v[168:171], v[224:227], v[10:13]
	v_mfma_f32_16x16x32_bf16 v[54:57], v[172:175], v[188:191], v[54:57]
	v_mfma_f32_16x16x32_bf16 v[54:57], v[176:179], v[192:195], v[54:57]
	v_mfma_f32_16x16x32_bf16 v[50:53], v[180:183], v[188:191], v[50:53]
	v_mfma_f32_16x16x32_bf16 v[50:53], v[184:187], v[192:195], v[50:53]
	v_mfma_f32_16x16x32_bf16 v[38:41], v[172:175], v[196:199], v[38:41]
	v_mfma_f32_16x16x32_bf16 v[38:41], v[176:179], v[200:203], v[38:41]
	v_mfma_f32_16x16x32_bf16 v[34:37], v[180:183], v[196:199], v[34:37]
	v_mfma_f32_16x16x32_bf16 v[34:37], v[184:187], v[200:203], v[34:37]
	v_mfma_f32_16x16x32_bf16 v[22:25], v[172:175], v[204:207], v[22:25]
	v_mfma_f32_16x16x32_bf16 v[22:25], v[176:179], v[216:219], v[22:25]
	v_mfma_f32_16x16x32_bf16 v[18:21], v[180:183], v[204:207], v[18:21]
	v_mfma_f32_16x16x32_bf16 v[18:21], v[184:187], v[216:219], v[18:21]
	v_mfma_f32_16x16x32_bf16 v[6:9], v[172:175], v[220:223], v[6:9]
	v_mfma_f32_16x16x32_bf16 v[6:9], v[176:179], v[224:227], v[6:9]
	v_mfma_f32_16x16x32_bf16 v[2:5], v[180:183], v[220:223], v[2:5]
	v_mfma_f32_16x16x32_bf16 v[2:5], v[184:187], v[224:227], v[2:5]
	s_barrier
	s_add_i32 s27, 0, 0x18000
	v_add_u32_e32 v149, s27, v146
	s_add_i32 s28, 0, 0x1c000
	ds_read_b128 v[140:143], v149
	ds_read_b128 v[150:153], v149 offset:1024
	ds_read_b128 v[154:157], v149 offset:2048
	ds_read_b128 v[168:171], v149 offset:3072
	v_add_u32_e32 v149, s28, v146
	ds_read_b128 v[172:175], v149
	ds_read_b128 v[176:179], v149 offset:1024
	ds_read_b128 v[180:183], v149 offset:2048
	ds_read_b128 v[184:187], v149 offset:3072
	s_add_u32 s0, s68, 0x158000
	s_addc_u32 s1, s69, 0
	s_mov_b32 m0, s71
	ds_read_b128 v[188:191], v148 offset:32768
	ds_read_b128 v[192:195], v148 offset:33792
	ds_read_b128 v[196:199], v148 offset:34816
	ds_read_b128 v[200:203], v148 offset:35840
	ds_read_b128 v[204:207], v148 offset:36864
	ds_read_b128 v[216:219], v148 offset:37888
	ds_read_b128 v[220:223], v148 offset:38912
	ds_read_b128 v[224:227], v148 offset:39936
	global_load_lds_dwordx4 v130, s[0:1]
	s_mov_b32 m0, s72
	s_nop 0
	global_load_lds_dwordx4 v132, s[0:1]
	s_waitcnt vmcnt(8)
	s_waitcnt lgkmcnt(0)
	s_barrier
	s_waitcnt lgkmcnt(0)
	v_mfma_f32_16x16x32_bf16 v[126:129], v[140:143], v[188:191], v[126:129]
	v_mfma_f32_16x16x32_bf16 v[126:129], v[150:153], v[192:195], v[126:129]
	v_mfma_f32_16x16x32_bf16 v[122:125], v[154:157], v[188:191], v[122:125]
	v_mfma_f32_16x16x32_bf16 v[122:125], v[168:171], v[192:195], v[122:125]
	v_mfma_f32_16x16x32_bf16 v[110:113], v[140:143], v[196:199], v[110:113]
	v_mfma_f32_16x16x32_bf16 v[110:113], v[150:153], v[200:203], v[110:113]
	v_mfma_f32_16x16x32_bf16 v[106:109], v[154:157], v[196:199], v[106:109]
	v_mfma_f32_16x16x32_bf16 v[106:109], v[168:171], v[200:203], v[106:109]
	v_mfma_f32_16x16x32_bf16 v[94:97], v[140:143], v[204:207], v[94:97]
	v_mfma_f32_16x16x32_bf16 v[94:97], v[150:153], v[216:219], v[94:97]
	v_mfma_f32_16x16x32_bf16 v[90:93], v[154:157], v[204:207], v[90:93]
	v_mfma_f32_16x16x32_bf16 v[90:93], v[168:171], v[216:219], v[90:93]
	v_mfma_f32_16x16x32_bf16 v[78:81], v[140:143], v[220:223], v[78:81]
	v_mfma_f32_16x16x32_bf16 v[78:81], v[150:153], v[224:227], v[78:81]
	v_mfma_f32_16x16x32_bf16 v[74:77], v[154:157], v[220:223], v[74:77]
	v_mfma_f32_16x16x32_bf16 v[74:77], v[168:171], v[224:227], v[74:77]
	v_mfma_f32_16x16x32_bf16 v[118:121], v[172:175], v[188:191], v[118:121]
	v_mfma_f32_16x16x32_bf16 v[118:121], v[176:179], v[192:195], v[118:121]
	v_mfma_f32_16x16x32_bf16 v[114:117], v[180:183], v[188:191], v[114:117]
	v_mfma_f32_16x16x32_bf16 v[114:117], v[184:187], v[192:195], v[114:117]
	v_mfma_f32_16x16x32_bf16 v[102:105], v[172:175], v[196:199], v[102:105]
	v_mfma_f32_16x16x32_bf16 v[102:105], v[176:179], v[200:203], v[102:105]
	v_mfma_f32_16x16x32_bf16 v[98:101], v[180:183], v[196:199], v[98:101]
	v_mfma_f32_16x16x32_bf16 v[98:101], v[184:187], v[200:203], v[98:101]
	v_mfma_f32_16x16x32_bf16 v[86:89], v[172:175], v[204:207], v[86:89]
	v_mfma_f32_16x16x32_bf16 v[86:89], v[176:179], v[216:219], v[86:89]
	v_mfma_f32_16x16x32_bf16 v[82:85], v[180:183], v[204:207], v[82:85]
	v_mfma_f32_16x16x32_bf16 v[82:85], v[184:187], v[216:219], v[82:85]
	v_mfma_f32_16x16x32_bf16 v[70:73], v[172:175], v[220:223], v[70:73]
	v_mfma_f32_16x16x32_bf16 v[70:73], v[176:179], v[224:227], v[70:73]
	v_mfma_f32_16x16x32_bf16 v[66:69], v[180:183], v[220:223], v[66:69]
	v_mfma_f32_16x16x32_bf16 v[66:69], v[184:187], v[224:227], v[66:69]
	s_barrier
	s_add_i32 s0, s27, s58
	s_add_u32 s100, s14, 0x80
	s_addc_u32 s101, s15, 0
	s_mov_b32 m0, s0
	ds_read_b128 v[188:191], v148 offset:49152
	ds_read_b128 v[192:195], v148 offset:50176
	ds_read_b128 v[196:199], v148 offset:51200
	ds_read_b128 v[200:203], v148 offset:52224
	ds_read_b128 v[204:207], v148 offset:53248
	ds_read_b128 v[216:219], v148 offset:54272
	ds_read_b128 v[220:223], v148 offset:55296
	ds_read_b128 v[224:227], v148 offset:56320
	global_load_lds_dwordx4 v158, s[100:101]
	s_add_i32 m0, s0, 0x2000
	s_add_u32 s0, s14, 0x158080
	s_addc_u32 s1, s15, 0
	s_add_i32 s14, s28, s58
	global_load_lds_dwordx4 v134, s[100:101]
	s_add_u32 s100, s68, 0x80
	s_addc_u32 s101, s69, 0
	s_mov_b32 m0, s14
	s_nop 0
	global_load_lds_dwordx4 v158, s[0:1]
	s_add_i32 m0, s14, 0x2000
	s_nop 0
	global_load_lds_dwordx4 v134, s[0:1]
	s_mov_b32 m0, s73
	s_nop 0
	global_load_lds_dwordx4 v130, s[100:101]
	s_mov_b32 m0, s74
	s_nop 0
	global_load_lds_dwordx4 v132, s[100:101]
	s_waitcnt vmcnt(8)
	s_waitcnt lgkmcnt(0)
	s_barrier
	s_waitcnt lgkmcnt(0)
	v_mfma_f32_16x16x32_bf16 v[62:65], v[140:143], v[188:191], v[62:65]
	v_mfma_f32_16x16x32_bf16 v[62:65], v[150:153], v[192:195], v[62:65]
	v_mfma_f32_16x16x32_bf16 v[58:61], v[154:157], v[188:191], v[58:61]
	v_mfma_f32_16x16x32_bf16 v[58:61], v[168:171], v[192:195], v[58:61]
	v_mfma_f32_16x16x32_bf16 v[46:49], v[140:143], v[196:199], v[46:49]
	v_mfma_f32_16x16x32_bf16 v[46:49], v[150:153], v[200:203], v[46:49]
	v_mfma_f32_16x16x32_bf16 v[42:45], v[154:157], v[196:199], v[42:45]
	v_mfma_f32_16x16x32_bf16 v[42:45], v[168:171], v[200:203], v[42:45]
	v_mfma_f32_16x16x32_bf16 v[30:33], v[140:143], v[204:207], v[30:33]
	v_mfma_f32_16x16x32_bf16 v[30:33], v[150:153], v[216:219], v[30:33]
	v_mfma_f32_16x16x32_bf16 v[26:29], v[154:157], v[204:207], v[26:29]
	v_mfma_f32_16x16x32_bf16 v[26:29], v[168:171], v[216:219], v[26:29]
	v_mfma_f32_16x16x32_bf16 v[14:17], v[140:143], v[220:223], v[14:17]
	v_mfma_f32_16x16x32_bf16 v[14:17], v[150:153], v[224:227], v[14:17]
	v_mfma_f32_16x16x32_bf16 v[10:13], v[154:157], v[220:223], v[10:13]
	v_mfma_f32_16x16x32_bf16 v[10:13], v[168:171], v[224:227], v[10:13]
	v_mfma_f32_16x16x32_bf16 v[54:57], v[172:175], v[188:191], v[54:57]
	v_mfma_f32_16x16x32_bf16 v[54:57], v[176:179], v[192:195], v[54:57]
	v_mfma_f32_16x16x32_bf16 v[50:53], v[180:183], v[188:191], v[50:53]
	v_mfma_f32_16x16x32_bf16 v[50:53], v[184:187], v[192:195], v[50:53]
	v_mfma_f32_16x16x32_bf16 v[38:41], v[172:175], v[196:199], v[38:41]
	v_mfma_f32_16x16x32_bf16 v[38:41], v[176:179], v[200:203], v[38:41]
	v_mfma_f32_16x16x32_bf16 v[34:37], v[180:183], v[196:199], v[34:37]
	v_mfma_f32_16x16x32_bf16 v[34:37], v[184:187], v[200:203], v[34:37]
	s_add_u32 s24, s24, 0x100
	v_mfma_f32_16x16x32_bf16 v[22:25], v[172:175], v[204:207], v[22:25]
	s_addc_u32 s25, s25, 0
	v_mfma_f32_16x16x32_bf16 v[22:25], v[176:179], v[216:219], v[22:25]
	s_mov_b64 s[0:1], s[36:37]
	v_mfma_f32_16x16x32_bf16 v[18:21], v[180:183], v[204:207], v[18:21]
	s_add_i32 s26, s26, 2
	v_mfma_f32_16x16x32_bf16 v[18:21], v[184:187], v[216:219], v[18:21]
	s_cmpk_gt_u32 s26, 0x53
	v_mfma_f32_16x16x32_bf16 v[6:9], v[172:175], v[220:223], v[6:9]
	v_mfma_f32_16x16x32_bf16 v[6:9], v[176:179], v[224:227], v[6:9]
	v_mfma_f32_16x16x32_bf16 v[2:5], v[180:183], v[220:223], v[2:5]
	v_mfma_f32_16x16x32_bf16 v[2:5], v[184:187], v[224:227], v[2:5]
	s_barrier
	s_cbranch_scc0 .Lsp_LBB0353
	s_and_b64 vcc, exec, s[12:13]
	s_cbranch_vccz .LBB0_356
	s_barrier
